# adds: grid barrier between mixer phase and LRU pass C replaced by a 16-workgroup same-head release/acquire counter (agent-scope sc1 AGG stores/loads), so pass C starts per workgroup as soon as its que
# speedup vs baseline: 1.0146x; 1.0146x over previous
.LBB0_359:
	s_waitcnt lgkmcnt(0)
	s_barrier
	s_and_saveexec_b64 s[46:47], s[44:45]
	s_cbranch_execz .LBB0_344
	ds_read_b64 v[0:1], v105
	ds_read_b64 v[2:3], v106
	ds_read_b64 v[4:5], v107
	ds_read_b64 v[6:7], v108
	s_waitcnt lgkmcnt(3)
	v_fma_f32 v8, 0, v0, v1
	s_waitcnt lgkmcnt(2)
	v_pk_mul_f32 v[0:1], v[0:1], v[2:3]
	v_fmac_f32_e32 v3, v2, v8
	s_waitcnt lgkmcnt(1)
	v_fma_f32 v3, v4, v3, v5
	v_mov_b32_e32 v2, v0
	v_mov_b32_e32 v8, v4
	s_waitcnt lgkmcnt(0)
	v_mov_b32_e32 v9, v6
	v_pk_mul_f32 v[0:1], v[0:1], v[4:5]
	v_pk_fma_f32 v[2:3], v[2:3], v[8:9], v[6:7]
	v_pk_mul_f32 v[0:1], v[0:1], v[6:7]
	s_nop 0
	v_mov_b32_e32 v1, v3
	global_store_dwordx2 v[66:67], v[0:1], off sc1
	s_branch .LBB0_344
.LBB0_361:
	s_waitcnt vmcnt(0)
	s_barrier
	s_and_saveexec_b64 s[100:101], s[56:57]
	s_and_b32 s98, s2, 15
	s_lshl_b32 s99, s96, 4
	s_add_i32 s98, s98, s99
	s_lshl_b32 s98, s98, 2
	s_add_u32 s98, s98, 0x16370d80
	s_add_u32 s98, s68, s98
	s_addc_u32 s99, s69, 0
	v_mov_b32_e32 v246, 0
	v_mov_b32_e32 v247, 1
	global_atomic_add v246, v247, s[98:99]
	s_or_b64 exec, exec, s[100:101]
	v_writelane_b32 v242, s10, 48
	s_and_b64 s[0:1], s[10:11], exec
	s_cselect_b32 s87, 0, 4
	s_lshl_b32 s92, s96, 1
	s_xor_b32 s91, s87, 0x104
	s_lshl_b64 s[0:1], s[92:93], 2
	v_readlane_b32 s4, v243, 24
	s_add_u32 s46, s4, s0
	v_readlane_b32 s0, v243, 25
	s_addc_u32 s47, s0, s1
	s_lshl_b32 s0, s87, 1
	v_writelane_b32 v242, s11, 49
	s_addk_i32 s0, 0xfefc
	v_writelane_b32 v242, s0, 51
	s_mul_i32 s92, s96, 0x3e00
	v_readlane_b32 s4, v242, 32
	s_lshl_b32 s97, s91, 1
	s_cmp_eq_u32 s87, 0
	s_cselect_b32 s98, 8, 0
	s_add_i32 s97, s97, s98
	s_lshl_b64 s[0:1], s[92:93], 2
	v_readlane_b32 s6, v242, 34
	v_readlane_b32 s7, v242, 35
	s_add_u32 s50, s6, s0
	v_readlane_b32 s5, v242, 33
	s_addc_u32 s51, s7, s1
	s_lshl_b32 s52, s96, 9
	s_mov_b32 s53, s93
	v_readlane_b32 s10, v242, 38
	s_lshl_b64 s[4:5], s[52:53], 2
	v_readlane_b32 s11, v242, 39
	s_add_u32 s54, s10, s4
	s_addc_u32 s55, s11, s5
	v_readlane_b32 s12, v242, 26
	v_readlane_b32 s13, v242, 27
	s_add_u32 s58, s12, s4
	v_readlane_b32 s14, v242, 28
	s_addc_u32 s59, s13, s5
	s_lshl_b32 s53, s96, 3
	v_readlane_b32 s15, v242, 29
	s_add_u32 s0, s14, s4
	s_addc_u32 s1, s15, s5
	v_readlane_b32 s6, v242, 24
	v_readlane_b32 s7, v242, 25
	s_add_u32 s72, s6, s4
	s_addc_u32 s73, s7, s5
	v_readlane_b32 s8, v242, 36
	v_readlane_b32 s9, v242, 37
	s_branch .LBB0_364

.LBB0_431:
	s_barrier
	s_and_saveexec_b64 s[100:101], s[56:57]
	s_cbranch_execz .Lhw_done
	s_and_b32 s98, s2, 15
	s_lshl_b32 s99, s96, 4
	s_add_i32 s98, s98, s99
	s_lshl_b32 s98, s98, 2
	s_add_u32 s98, s98, 0x16370d80
	s_add_u32 s98, s68, s98
	s_addc_u32 s99, s69, 0
	v_mov_b32_e32 v247, 0
.Lhw_spin:
	v_mov_b32_e32 v246, 0
	global_load_dword v246, v246, s[98:99] sc1
	s_waitcnt vmcnt(0)
	v_cmp_gt_u32_e32 vcc, 16, v246
	s_cbranch_vccz .Lhw_got
	s_sleep 2
	v_add_u32_e32 v247, 1, v247
	v_cmp_gt_u32_e32 vcc, 0x2000, v247
	s_cbranch_vccnz .Lhw_spin
.Lhw_got:
.Lhw_done:
	s_or_b64 exec, exec, s[100:101]
	s_barrier
	s_mul_i32 s0, s96, 5
	s_add_i32 s4, s0, 5
	s_branch .LBB0_577
	s_mul_i32 s0, s96, 5
	s_add_i32 s4, s0, 4
	s_cmp_lt_i32 s4, s71
	s_cselect_b64 s[0:1], -1, 0
	s_and_b64 s[6:7], s[28:29], s[0:1]
	s_andn2_b64 vcc, exec, s[6:7]
	s_cbranch_vccnz .LBB0_497
	v_readlane_b32 s6, v244, 18
	v_readlane_b32 s7, v244, 19
	s_andn2_b64 vcc, exec, s[6:7]
	s_cbranch_vccnz .LBB0_444
	s_barrier
	s_mov_b64 s[40:41], exec
	v_readlane_b32 s6, v242, 6
	v_readlane_b32 s7, v242, 7
	s_and_b64 s[6:7], s[40:41], s[6:7]
	s_mov_b64 exec, s[6:7]
	s_cbranch_execz .LBB0_443
	v_readlane_b32 s6, v244, 0
	v_readlane_b32 s7, v244, 1
	buffer_wbl2 sc1
	s_waitcnt vmcnt(0)
	s_load_dwordx2 s[42:43], s[6:7], 0x58
	s_mov_b64 s[44:45], exec
	v_mbcnt_lo_u32_b32 v1, s44, 0
	v_mbcnt_hi_u32_b32 v1, s45, v1
	v_cmp_eq_u32_e32 vcc, 0, v1
	s_waitcnt lgkmcnt(0)
	global_load_dword v0, v145, s[42:43] offset:40
	s_and_saveexec_b64 s[46:47], vcc
	s_cbranch_execz .LBB0_436
	s_bcnt1_i32_b64 s5, s[44:45]
	v_mov_b32_e32 v2, s5
	global_atomic_add v2, v145, v2, s[42:43] offset:32 sc0

.Lcf_var_0:
	s_add_u32 s100, s68, 0x16064c40
	s_addc_u32 s101, s69, 0
	global_load_dwordx2 v[48:49], v20, s[100:101] sc1
	s_add_u32 s100, s68, 0x16066c40
	s_addc_u32 s101, s69, 0
	global_load_dwordx2 v[50:51], v20, s[100:101] sc1
	s_add_u32 s100, s68, 0x16068c40
	s_addc_u32 s101, s69, 0
	global_load_dwordx2 v[52:53], v20, s[100:101] sc1
	s_add_u32 s100, s68, 0x1606ac40
	s_addc_u32 s101, s69, 0
	global_load_dwordx2 v[54:55], v20, s[100:101] sc1
	s_add_u32 s100, s68, 0x1606cc40
	s_addc_u32 s101, s69, 0
	global_load_dwordx2 v[56:57], v20, s[100:101] sc1
	s_add_u32 s100, s68, 0x1606ec40
	s_addc_u32 s101, s69, 0
	global_load_dwordx2 v[58:59], v20, s[100:101] sc1
	s_add_u32 s100, s68, 0x16070c40
	s_addc_u32 s101, s69, 0
	global_load_dwordx2 v[60:61], v20, s[100:101] sc1
	s_add_u32 s100, s68, 0x16072c40
	s_addc_u32 s101, s69, 0
	global_load_dwordx2 v[62:63], v20, s[100:101] sc1
	s_add_u32 s100, s68, 0x16074c40
	s_addc_u32 s101, s69, 0
	global_load_dwordx2 v[64:65], v20, s[100:101] sc1
	s_add_u32 s100, s68, 0x16076c40
	s_addc_u32 s101, s69, 0
	global_load_dwordx2 v[66:67], v20, s[100:101] sc1
	s_add_u32 s100, s68, 0x16078c40
	s_addc_u32 s101, s69, 0
	global_load_dwordx2 v[68:69], v20, s[100:101] sc1
	s_add_u32 s100, s68, 0x1607ac40
	s_addc_u32 s101, s69, 0
	global_load_dwordx2 v[70:71], v20, s[100:101] sc1
	s_add_u32 s100, s68, 0x1607cc40
	s_addc_u32 s101, s69, 0
	global_load_dwordx2 v[78:79], v20, s[100:101] sc1
	s_add_u32 s100, s68, 0x1607ec40
	s_addc_u32 s101, s69, 0
	global_load_dwordx2 v[80:81], v20, s[100:101] sc1
	s_add_u32 s100, s68, 0x16080c40
	s_addc_u32 s101, s69, 0
	global_load_dwordx2 v[82:83], v20, s[100:101] sc1
	s_add_u32 s100, s68, 0x16082c40
	s_addc_u32 s101, s69, 0
	global_load_dwordx2 v[84:85], v20, s[100:101] sc1
	s_add_u32 s100, s68, 0x16084c40
	s_addc_u32 s101, s69, 0
	global_load_dwordx2 v[86:87], v20, s[100:101] sc1
	s_add_u32 s100, s68, 0x16086c40
	s_addc_u32 s101, s69, 0
	global_load_dwordx2 v[88:89], v20, s[100:101] sc1
	s_add_u32 s100, s68, 0x16088c40
	s_addc_u32 s101, s69, 0
	global_load_dwordx2 v[90:91], v20, s[100:101] sc1
	s_add_u32 s100, s68, 0x1608ac40
	s_addc_u32 s101, s69, 0
	global_load_dwordx2 v[92:93], v20, s[100:101] sc1
	s_add_u32 s100, s68, 0x1608cc40
	s_addc_u32 s101, s69, 0
	global_load_dwordx2 v[94:95], v20, s[100:101] sc1
	s_add_u32 s100, s68, 0x1608ec40
	s_addc_u32 s101, s69, 0
	global_load_dwordx2 v[96:97], v20, s[100:101] sc1
	s_add_u32 s100, s68, 0x16090c40
	s_addc_u32 s101, s69, 0
	global_load_dwordx2 v[98:99], v20, s[100:101] sc1
	s_add_u32 s100, s68, 0x16092c40
	s_addc_u32 s101, s69, 0
	global_load_dwordx2 v[100:101], v20, s[100:101] sc1
	s_add_u32 s100, s68, 0x16094c40
	s_addc_u32 s101, s69, 0
	global_load_dwordx2 v[102:103], v20, s[100:101] sc1
	s_add_u32 s100, s68, 0x16096c40
	s_addc_u32 s101, s69, 0
	global_load_dwordx2 v[104:105], v20, s[100:101] sc1
	s_add_u32 s100, s68, 0x16098c40
	s_addc_u32 s101, s69, 0
	global_load_dwordx2 v[106:107], v20, s[100:101] sc1
	s_add_u32 s100, s68, 0x1609ac40
	s_addc_u32 s101, s69, 0
	global_load_dwordx2 v[108:109], v20, s[100:101] sc1
	s_add_u32 s100, s68, 0x1609cc40
	s_addc_u32 s101, s69, 0
	global_load_dwordx2 v[110:111], v20, s[100:101] sc1
	s_add_u32 s100, s68, 0x1609ec40
	s_addc_u32 s101, s69, 0
	global_load_dwordx2 v[112:113], v20, s[100:101] sc1
	s_add_u32 s100, s68, 0x160a0c40
	s_addc_u32 s101, s69, 0
	global_load_dwordx2 v[114:115], v20, s[100:101] sc1
	s_add_u32 s100, s68, 0x160a2c40
	s_addc_u32 s101, s69, 0
	global_load_dwordx2 v[116:117], v20, s[100:101] sc1
	s_add_u32 s100, s68, 0x160a4c40
	s_addc_u32 s101, s69, 0
	global_load_dwordx2 v[118:119], v20, s[100:101] sc1
	v_mov_b32_e32 v24, 1.0
	v_mov_b32_e32 v25, 0
	s_waitcnt vmcnt(32)
	v_fma_f32 v25, v48, v25, v49
	v_mul_f32_e32 v24, v24, v48
	s_waitcnt vmcnt(31)
	v_fma_f32 v25, v50, v25, v51
	v_mul_f32_e32 v24, v24, v50
	s_waitcnt vmcnt(30)
	v_fma_f32 v25, v52, v25, v53
	v_mul_f32_e32 v24, v24, v52
	s_waitcnt vmcnt(29)
	v_fma_f32 v25, v54, v25, v55
	v_mul_f32_e32 v24, v24, v54
	s_waitcnt vmcnt(28)
	v_fma_f32 v25, v56, v25, v57
	v_mul_f32_e32 v24, v24, v56
	s_waitcnt vmcnt(27)
	v_fma_f32 v25, v58, v25, v59
	v_mul_f32_e32 v24, v24, v58
	s_waitcnt vmcnt(26)
	v_fma_f32 v25, v60, v25, v61
	v_mul_f32_e32 v24, v24, v60
	s_waitcnt vmcnt(25)
	v_fma_f32 v25, v62, v25, v63
	v_mul_f32_e32 v24, v24, v62
	s_waitcnt vmcnt(24)
	v_fma_f32 v25, v64, v25, v65
	v_mul_f32_e32 v24, v24, v64
	s_waitcnt vmcnt(23)
	v_fma_f32 v25, v66, v25, v67
	v_mul_f32_e32 v24, v24, v66
	s_waitcnt vmcnt(22)
	v_fma_f32 v25, v68, v25, v69
	v_mul_f32_e32 v24, v24, v68
	s_waitcnt vmcnt(21)
	v_fma_f32 v25, v70, v25, v71
	v_mul_f32_e32 v24, v24, v70
	s_waitcnt vmcnt(20)
	v_fma_f32 v25, v78, v25, v79
	v_mul_f32_e32 v24, v24, v78
	s_waitcnt vmcnt(19)
	v_fma_f32 v25, v80, v25, v81
	v_mul_f32_e32 v24, v24, v80
	s_waitcnt vmcnt(18)
	v_fma_f32 v25, v82, v25, v83
	v_mul_f32_e32 v24, v24, v82
	s_waitcnt vmcnt(17)
	v_fma_f32 v25, v84, v25, v85
	v_mul_f32_e32 v24, v24, v84
	s_waitcnt vmcnt(16)
	v_fma_f32 v25, v86, v25, v87
	v_mul_f32_e32 v24, v24, v86
	s_waitcnt vmcnt(15)
	v_fma_f32 v25, v88, v25, v89
	v_mul_f32_e32 v24, v24, v88
	s_waitcnt vmcnt(14)
	v_fma_f32 v25, v90, v25, v91
	v_mul_f32_e32 v24, v24, v90
	s_waitcnt vmcnt(13)
	v_fma_f32 v25, v92, v25, v93
	v_mul_f32_e32 v24, v24, v92
	s_waitcnt vmcnt(12)
	v_fma_f32 v25, v94, v25, v95
	v_mul_f32_e32 v24, v24, v94
	s_waitcnt vmcnt(11)
	v_fma_f32 v25, v96, v25, v97
	v_mul_f32_e32 v24, v24, v96
	s_waitcnt vmcnt(10)
	v_fma_f32 v25, v98, v25, v99
	v_mul_f32_e32 v24, v24, v98
	s_waitcnt vmcnt(9)
	v_fma_f32 v25, v100, v25, v101
	v_mul_f32_e32 v24, v24, v100
	s_waitcnt vmcnt(8)
	v_fma_f32 v25, v102, v25, v103
	v_mul_f32_e32 v24, v24, v102
	s_waitcnt vmcnt(7)
	v_fma_f32 v25, v104, v25, v105
	v_mul_f32_e32 v24, v24, v104
	s_waitcnt vmcnt(6)
	v_fma_f32 v25, v106, v25, v107
	v_mul_f32_e32 v24, v24, v106
	s_waitcnt vmcnt(5)
	v_fma_f32 v25, v108, v25, v109
	v_mul_f32_e32 v24, v24, v108
	s_waitcnt vmcnt(4)
	v_fma_f32 v25, v110, v25, v111
	v_mul_f32_e32 v24, v24, v110
	s_waitcnt vmcnt(3)
	v_fma_f32 v25, v112, v25, v113
	v_mul_f32_e32 v24, v24, v112
	s_waitcnt vmcnt(2)
	v_fma_f32 v25, v114, v25, v115
	v_mul_f32_e32 v24, v24, v114
	s_waitcnt vmcnt(1)
	v_fma_f32 v25, v116, v25, v117
	v_mul_f32_e32 v24, v24, v116
	s_waitcnt vmcnt(0)
	v_fma_f32 v25, v118, v25, v119
	v_mul_f32_e32 v24, v24, v118
	ds_write_b64 v22, v[24:25] offset:0
	s_waitcnt lgkmcnt(0)
	s_barrier
	v_mov_b32_e32 v26, 0
	s_cmp_eq_u32 s99, 0
	s_cbranch_scc0 .Lcf_skip_0_0
	s_add_u32 s100, s68, 0x1626cc40
	s_addc_u32 s101, s69, 0
	global_store_dword v21, v26, s[100:101]

.Lcf_var_1:
	s_add_u32 s100, s68, 0x160a6c40
	s_addc_u32 s101, s69, 0
	global_load_dwordx2 v[48:49], v20, s[100:101] sc1
	s_add_u32 s100, s68, 0x160a8c40
	s_addc_u32 s101, s69, 0
	global_load_dwordx2 v[50:51], v20, s[100:101] sc1
	s_add_u32 s100, s68, 0x160aac40
	s_addc_u32 s101, s69, 0
	global_load_dwordx2 v[52:53], v20, s[100:101] sc1
	s_add_u32 s100, s68, 0x160acc40
	s_addc_u32 s101, s69, 0
	global_load_dwordx2 v[54:55], v20, s[100:101] sc1
	s_add_u32 s100, s68, 0x160aec40
	s_addc_u32 s101, s69, 0
	global_load_dwordx2 v[56:57], v20, s[100:101] sc1
	s_add_u32 s100, s68, 0x160b0c40
	s_addc_u32 s101, s69, 0
	global_load_dwordx2 v[58:59], v20, s[100:101] sc1
	s_add_u32 s100, s68, 0x160b2c40
	s_addc_u32 s101, s69, 0
	global_load_dwordx2 v[60:61], v20, s[100:101] sc1
	s_add_u32 s100, s68, 0x160b4c40
	s_addc_u32 s101, s69, 0
	global_load_dwordx2 v[62:63], v20, s[100:101] sc1
	s_add_u32 s100, s68, 0x160b6c40
	s_addc_u32 s101, s69, 0
	global_load_dwordx2 v[64:65], v20, s[100:101] sc1
	s_add_u32 s100, s68, 0x160b8c40
	s_addc_u32 s101, s69, 0
	global_load_dwordx2 v[66:67], v20, s[100:101] sc1
	s_add_u32 s100, s68, 0x160bac40
	s_addc_u32 s101, s69, 0
	global_load_dwordx2 v[68:69], v20, s[100:101] sc1
	s_add_u32 s100, s68, 0x160bcc40
	s_addc_u32 s101, s69, 0
	global_load_dwordx2 v[70:71], v20, s[100:101] sc1
	s_add_u32 s100, s68, 0x160bec40
	s_addc_u32 s101, s69, 0
	global_load_dwordx2 v[78:79], v20, s[100:101] sc1
	s_add_u32 s100, s68, 0x160c0c40
	s_addc_u32 s101, s69, 0
	global_load_dwordx2 v[80:81], v20, s[100:101] sc1
	s_add_u32 s100, s68, 0x160c2c40
	s_addc_u32 s101, s69, 0
	global_load_dwordx2 v[82:83], v20, s[100:101] sc1
	s_add_u32 s100, s68, 0x160c4c40
	s_addc_u32 s101, s69, 0
	global_load_dwordx2 v[84:85], v20, s[100:101] sc1
	s_add_u32 s100, s68, 0x160c6c40
	s_addc_u32 s101, s69, 0
	global_load_dwordx2 v[86:87], v20, s[100:101] sc1
	s_add_u32 s100, s68, 0x160c8c40
	s_addc_u32 s101, s69, 0
	global_load_dwordx2 v[88:89], v20, s[100:101] sc1
	s_add_u32 s100, s68, 0x160cac40
	s_addc_u32 s101, s69, 0
	global_load_dwordx2 v[90:91], v20, s[100:101] sc1
	s_add_u32 s100, s68, 0x160ccc40
	s_addc_u32 s101, s69, 0
	global_load_dwordx2 v[92:93], v20, s[100:101] sc1
	s_add_u32 s100, s68, 0x160cec40
	s_addc_u32 s101, s69, 0
	global_load_dwordx2 v[94:95], v20, s[100:101] sc1
	s_add_u32 s100, s68, 0x160d0c40
	s_addc_u32 s101, s69, 0
	global_load_dwordx2 v[96:97], v20, s[100:101] sc1
	s_add_u32 s100, s68, 0x160d2c40
	s_addc_u32 s101, s69, 0
	global_load_dwordx2 v[98:99], v20, s[100:101] sc1
	s_add_u32 s100, s68, 0x160d4c40
	s_addc_u32 s101, s69, 0
	global_load_dwordx2 v[100:101], v20, s[100:101] sc1
	s_add_u32 s100, s68, 0x160d6c40
	s_addc_u32 s101, s69, 0
	global_load_dwordx2 v[102:103], v20, s[100:101] sc1
	s_add_u32 s100, s68, 0x160d8c40
	s_addc_u32 s101, s69, 0
	global_load_dwordx2 v[104:105], v20, s[100:101] sc1
	s_add_u32 s100, s68, 0x160dac40
	s_addc_u32 s101, s69, 0
	global_load_dwordx2 v[106:107], v20, s[100:101] sc1
	s_add_u32 s100, s68, 0x160dcc40
	s_addc_u32 s101, s69, 0
	global_load_dwordx2 v[108:109], v20, s[100:101] sc1
	s_add_u32 s100, s68, 0x160dec40
	s_addc_u32 s101, s69, 0
	global_load_dwordx2 v[110:111], v20, s[100:101] sc1
	s_add_u32 s100, s68, 0x160e0c40
	s_addc_u32 s101, s69, 0
	global_load_dwordx2 v[112:113], v20, s[100:101] sc1
	s_add_u32 s100, s68, 0x160e2c40
	s_addc_u32 s101, s69, 0
	global_load_dwordx2 v[114:115], v20, s[100:101] sc1
	s_add_u32 s100, s68, 0x160e4c40
	s_addc_u32 s101, s69, 0
	global_load_dwordx2 v[116:117], v20, s[100:101] sc1
	s_add_u32 s100, s68, 0x160e6c40
	s_addc_u32 s101, s69, 0
	global_load_dwordx2 v[118:119], v20, s[100:101] sc1
	v_mov_b32_e32 v24, 1.0
	v_mov_b32_e32 v25, 0
	s_waitcnt vmcnt(32)
	v_fma_f32 v25, v48, v25, v49
	v_mul_f32_e32 v24, v24, v48
	s_waitcnt vmcnt(31)
	v_fma_f32 v25, v50, v25, v51
	v_mul_f32_e32 v24, v24, v50
	s_waitcnt vmcnt(30)
	v_fma_f32 v25, v52, v25, v53
	v_mul_f32_e32 v24, v24, v52
	s_waitcnt vmcnt(29)
	v_fma_f32 v25, v54, v25, v55
	v_mul_f32_e32 v24, v24, v54
	s_waitcnt vmcnt(28)
	v_fma_f32 v25, v56, v25, v57
	v_mul_f32_e32 v24, v24, v56
	s_waitcnt vmcnt(27)
	v_fma_f32 v25, v58, v25, v59
	v_mul_f32_e32 v24, v24, v58
	s_waitcnt vmcnt(26)
	v_fma_f32 v25, v60, v25, v61
	v_mul_f32_e32 v24, v24, v60
	s_waitcnt vmcnt(25)
	v_fma_f32 v25, v62, v25, v63
	v_mul_f32_e32 v24, v24, v62
	s_waitcnt vmcnt(24)
	v_fma_f32 v25, v64, v25, v65
	v_mul_f32_e32 v24, v24, v64
	s_waitcnt vmcnt(23)
	v_fma_f32 v25, v66, v25, v67
	v_mul_f32_e32 v24, v24, v66
	s_waitcnt vmcnt(22)
	v_fma_f32 v25, v68, v25, v69
	v_mul_f32_e32 v24, v24, v68
	s_waitcnt vmcnt(21)
	v_fma_f32 v25, v70, v25, v71
	v_mul_f32_e32 v24, v24, v70
	s_waitcnt vmcnt(20)
	v_fma_f32 v25, v78, v25, v79
	v_mul_f32_e32 v24, v24, v78
	s_waitcnt vmcnt(19)
	v_fma_f32 v25, v80, v25, v81
	v_mul_f32_e32 v24, v24, v80
	s_waitcnt vmcnt(18)
	v_fma_f32 v25, v82, v25, v83
	v_mul_f32_e32 v24, v24, v82
	s_waitcnt vmcnt(17)
	v_fma_f32 v25, v84, v25, v85
	v_mul_f32_e32 v24, v24, v84
	s_waitcnt vmcnt(16)
	v_fma_f32 v25, v86, v25, v87
	v_mul_f32_e32 v24, v24, v86
	s_waitcnt vmcnt(15)
	v_fma_f32 v25, v88, v25, v89
	v_mul_f32_e32 v24, v24, v88
	s_waitcnt vmcnt(14)
	v_fma_f32 v25, v90, v25, v91
	v_mul_f32_e32 v24, v24, v90
	s_waitcnt vmcnt(13)
	v_fma_f32 v25, v92, v25, v93
	v_mul_f32_e32 v24, v24, v92
	s_waitcnt vmcnt(12)
	v_fma_f32 v25, v94, v25, v95
	v_mul_f32_e32 v24, v24, v94
	s_waitcnt vmcnt(11)
	v_fma_f32 v25, v96, v25, v97
	v_mul_f32_e32 v24, v24, v96
	s_waitcnt vmcnt(10)
	v_fma_f32 v25, v98, v25, v99
	v_mul_f32_e32 v24, v24, v98
	s_waitcnt vmcnt(9)
	v_fma_f32 v25, v100, v25, v101
	v_mul_f32_e32 v24, v24, v100
	s_waitcnt vmcnt(8)
	v_fma_f32 v25, v102, v25, v103
	v_mul_f32_e32 v24, v24, v102
	s_waitcnt vmcnt(7)
	v_fma_f32 v25, v104, v25, v105
	v_mul_f32_e32 v24, v24, v104
	s_waitcnt vmcnt(6)
	v_fma_f32 v25, v106, v25, v107
	v_mul_f32_e32 v24, v24, v106
	s_waitcnt vmcnt(5)
	v_fma_f32 v25, v108, v25, v109
	v_mul_f32_e32 v24, v24, v108
	s_waitcnt vmcnt(4)
	v_fma_f32 v25, v110, v25, v111
	v_mul_f32_e32 v24, v24, v110
	s_waitcnt vmcnt(3)
	v_fma_f32 v25, v112, v25, v113
	v_mul_f32_e32 v24, v24, v112
	s_waitcnt vmcnt(2)
	v_fma_f32 v25, v114, v25, v115
	v_mul_f32_e32 v24, v24, v114
	s_waitcnt vmcnt(1)
	v_fma_f32 v25, v116, v25, v117
	v_mul_f32_e32 v24, v24, v116
	s_waitcnt vmcnt(0)
	v_fma_f32 v25, v118, v25, v119
	v_mul_f32_e32 v24, v24, v118
	ds_write_b64 v22, v[24:25] offset:512
	s_waitcnt lgkmcnt(0)
	s_barrier
	v_mov_b32_e32 v26, 0
	ds_read_b64 v[28:29], v22 offset:0
	s_waitcnt lgkmcnt(0)
	v_fma_f32 v26, v28, v26, v29
	s_cmp_eq_u32 s99, 1
	s_cbranch_scc0 .Lcf_skip_1_0
	s_add_u32 s100, s68, 0x1628dc40
	s_addc_u32 s101, s69, 0
	global_store_dword v21, v26, s[100:101]

.Lcf_var_2:
	s_add_u32 s100, s68, 0x160e8c40
	s_addc_u32 s101, s69, 0
	global_load_dwordx2 v[48:49], v20, s[100:101] sc1
	s_add_u32 s100, s68, 0x160eac40
	s_addc_u32 s101, s69, 0
	global_load_dwordx2 v[50:51], v20, s[100:101] sc1
	s_add_u32 s100, s68, 0x160ecc40
	s_addc_u32 s101, s69, 0
	global_load_dwordx2 v[52:53], v20, s[100:101] sc1
	s_add_u32 s100, s68, 0x160eec40
	s_addc_u32 s101, s69, 0
	global_load_dwordx2 v[54:55], v20, s[100:101] sc1
	s_add_u32 s100, s68, 0x160f0c40
	s_addc_u32 s101, s69, 0
	global_load_dwordx2 v[56:57], v20, s[100:101] sc1
	s_add_u32 s100, s68, 0x160f2c40
	s_addc_u32 s101, s69, 0
	global_load_dwordx2 v[58:59], v20, s[100:101] sc1
	s_add_u32 s100, s68, 0x160f4c40
	s_addc_u32 s101, s69, 0
	global_load_dwordx2 v[60:61], v20, s[100:101] sc1
	s_add_u32 s100, s68, 0x160f6c40
	s_addc_u32 s101, s69, 0
	global_load_dwordx2 v[62:63], v20, s[100:101] sc1
	s_add_u32 s100, s68, 0x160f8c40
	s_addc_u32 s101, s69, 0
	global_load_dwordx2 v[64:65], v20, s[100:101] sc1
	s_add_u32 s100, s68, 0x160fac40
	s_addc_u32 s101, s69, 0
	global_load_dwordx2 v[66:67], v20, s[100:101] sc1
	s_add_u32 s100, s68, 0x160fcc40
	s_addc_u32 s101, s69, 0
	global_load_dwordx2 v[68:69], v20, s[100:101] sc1
	s_add_u32 s100, s68, 0x160fec40
	s_addc_u32 s101, s69, 0
	global_load_dwordx2 v[70:71], v20, s[100:101] sc1
	s_add_u32 s100, s68, 0x16100c40
	s_addc_u32 s101, s69, 0
	global_load_dwordx2 v[78:79], v20, s[100:101] sc1
	s_add_u32 s100, s68, 0x16102c40
	s_addc_u32 s101, s69, 0
	global_load_dwordx2 v[80:81], v20, s[100:101] sc1
	s_add_u32 s100, s68, 0x16104c40
	s_addc_u32 s101, s69, 0
	global_load_dwordx2 v[82:83], v20, s[100:101] sc1
	s_add_u32 s100, s68, 0x16106c40
	s_addc_u32 s101, s69, 0
	global_load_dwordx2 v[84:85], v20, s[100:101] sc1
	s_add_u32 s100, s68, 0x16108c40
	s_addc_u32 s101, s69, 0
	global_load_dwordx2 v[86:87], v20, s[100:101] sc1
	s_add_u32 s100, s68, 0x1610ac40
	s_addc_u32 s101, s69, 0
	global_load_dwordx2 v[88:89], v20, s[100:101] sc1
	s_add_u32 s100, s68, 0x1610cc40
	s_addc_u32 s101, s69, 0
	global_load_dwordx2 v[90:91], v20, s[100:101] sc1
	s_add_u32 s100, s68, 0x1610ec40
	s_addc_u32 s101, s69, 0
	global_load_dwordx2 v[92:93], v20, s[100:101] sc1
	s_add_u32 s100, s68, 0x16110c40
	s_addc_u32 s101, s69, 0
	global_load_dwordx2 v[94:95], v20, s[100:101] sc1
	s_add_u32 s100, s68, 0x16112c40
	s_addc_u32 s101, s69, 0
	global_load_dwordx2 v[96:97], v20, s[100:101] sc1
	s_add_u32 s100, s68, 0x16114c40
	s_addc_u32 s101, s69, 0
	global_load_dwordx2 v[98:99], v20, s[100:101] sc1
	s_add_u32 s100, s68, 0x16116c40
	s_addc_u32 s101, s69, 0
	global_load_dwordx2 v[100:101], v20, s[100:101] sc1
	s_add_u32 s100, s68, 0x16118c40
	s_addc_u32 s101, s69, 0
	global_load_dwordx2 v[102:103], v20, s[100:101] sc1
	s_add_u32 s100, s68, 0x1611ac40
	s_addc_u32 s101, s69, 0
	global_load_dwordx2 v[104:105], v20, s[100:101] sc1
	s_add_u32 s100, s68, 0x1611cc40
	s_addc_u32 s101, s69, 0
	global_load_dwordx2 v[106:107], v20, s[100:101] sc1
	s_add_u32 s100, s68, 0x1611ec40
	s_addc_u32 s101, s69, 0
	global_load_dwordx2 v[108:109], v20, s[100:101] sc1
	s_add_u32 s100, s68, 0x16120c40
	s_addc_u32 s101, s69, 0
	global_load_dwordx2 v[110:111], v20, s[100:101] sc1
	s_add_u32 s100, s68, 0x16122c40
	s_addc_u32 s101, s69, 0
	global_load_dwordx2 v[112:113], v20, s[100:101] sc1
	s_add_u32 s100, s68, 0x16124c40
	s_addc_u32 s101, s69, 0
	global_load_dwordx2 v[114:115], v20, s[100:101] sc1
	s_add_u32 s100, s68, 0x16126c40
	s_addc_u32 s101, s69, 0
	global_load_dwordx2 v[116:117], v20, s[100:101] sc1
	s_add_u32 s100, s68, 0x16128c40
	s_addc_u32 s101, s69, 0
	global_load_dwordx2 v[118:119], v20, s[100:101] sc1
	v_mov_b32_e32 v24, 1.0
	v_mov_b32_e32 v25, 0
	s_waitcnt vmcnt(32)
	v_fma_f32 v25, v48, v25, v49
	v_mul_f32_e32 v24, v24, v48
	s_waitcnt vmcnt(31)
	v_fma_f32 v25, v50, v25, v51
	v_mul_f32_e32 v24, v24, v50
	s_waitcnt vmcnt(30)
	v_fma_f32 v25, v52, v25, v53
	v_mul_f32_e32 v24, v24, v52
	s_waitcnt vmcnt(29)
	v_fma_f32 v25, v54, v25, v55
	v_mul_f32_e32 v24, v24, v54
	s_waitcnt vmcnt(28)
	v_fma_f32 v25, v56, v25, v57
	v_mul_f32_e32 v24, v24, v56
	s_waitcnt vmcnt(27)
	v_fma_f32 v25, v58, v25, v59
	v_mul_f32_e32 v24, v24, v58
	s_waitcnt vmcnt(26)
	v_fma_f32 v25, v60, v25, v61
	v_mul_f32_e32 v24, v24, v60
	s_waitcnt vmcnt(25)
	v_fma_f32 v25, v62, v25, v63
	v_mul_f32_e32 v24, v24, v62
	s_waitcnt vmcnt(24)
	v_fma_f32 v25, v64, v25, v65
	v_mul_f32_e32 v24, v24, v64
	s_waitcnt vmcnt(23)
	v_fma_f32 v25, v66, v25, v67
	v_mul_f32_e32 v24, v24, v66
	s_waitcnt vmcnt(22)
	v_fma_f32 v25, v68, v25, v69
	v_mul_f32_e32 v24, v24, v68
	s_waitcnt vmcnt(21)
	v_fma_f32 v25, v70, v25, v71
	v_mul_f32_e32 v24, v24, v70
	s_waitcnt vmcnt(20)
	v_fma_f32 v25, v78, v25, v79
	v_mul_f32_e32 v24, v24, v78
	s_waitcnt vmcnt(19)
	v_fma_f32 v25, v80, v25, v81
	v_mul_f32_e32 v24, v24, v80
	s_waitcnt vmcnt(18)
	v_fma_f32 v25, v82, v25, v83
	v_mul_f32_e32 v24, v24, v82
	s_waitcnt vmcnt(17)
	v_fma_f32 v25, v84, v25, v85
	v_mul_f32_e32 v24, v24, v84
	s_waitcnt vmcnt(16)
	v_fma_f32 v25, v86, v25, v87
	v_mul_f32_e32 v24, v24, v86
	s_waitcnt vmcnt(15)
	v_fma_f32 v25, v88, v25, v89
	v_mul_f32_e32 v24, v24, v88
	s_waitcnt vmcnt(14)
	v_fma_f32 v25, v90, v25, v91
	v_mul_f32_e32 v24, v24, v90
	s_waitcnt vmcnt(13)
	v_fma_f32 v25, v92, v25, v93
	v_mul_f32_e32 v24, v24, v92
	s_waitcnt vmcnt(12)
	v_fma_f32 v25, v94, v25, v95
	v_mul_f32_e32 v24, v24, v94
	s_waitcnt vmcnt(11)
	v_fma_f32 v25, v96, v25, v97
	v_mul_f32_e32 v24, v24, v96
	s_waitcnt vmcnt(10)
	v_fma_f32 v25, v98, v25, v99
	v_mul_f32_e32 v24, v24, v98
	s_waitcnt vmcnt(9)
	v_fma_f32 v25, v100, v25, v101
	v_mul_f32_e32 v24, v24, v100
	s_waitcnt vmcnt(8)
	v_fma_f32 v25, v102, v25, v103
	v_mul_f32_e32 v24, v24, v102
	s_waitcnt vmcnt(7)
	v_fma_f32 v25, v104, v25, v105
	v_mul_f32_e32 v24, v24, v104
	s_waitcnt vmcnt(6)
	v_fma_f32 v25, v106, v25, v107
	v_mul_f32_e32 v24, v24, v106
	s_waitcnt vmcnt(5)
	v_fma_f32 v25, v108, v25, v109
	v_mul_f32_e32 v24, v24, v108
	s_waitcnt vmcnt(4)
	v_fma_f32 v25, v110, v25, v111
	v_mul_f32_e32 v24, v24, v110
	s_waitcnt vmcnt(3)
	v_fma_f32 v25, v112, v25, v113
	v_mul_f32_e32 v24, v24, v112
	s_waitcnt vmcnt(2)
	v_fma_f32 v25, v114, v25, v115
	v_mul_f32_e32 v24, v24, v114
	s_waitcnt vmcnt(1)
	v_fma_f32 v25, v116, v25, v117
	v_mul_f32_e32 v24, v24, v116
	s_waitcnt vmcnt(0)
	v_fma_f32 v25, v118, v25, v119
	v_mul_f32_e32 v24, v24, v118
	ds_write_b64 v22, v[24:25] offset:1024
	s_waitcnt lgkmcnt(0)
	s_barrier
	v_mov_b32_e32 v26, 0
	ds_read_b64 v[28:29], v22 offset:0
	s_waitcnt lgkmcnt(0)
	v_fma_f32 v26, v28, v26, v29
	ds_read_b64 v[28:29], v22 offset:512
	s_waitcnt lgkmcnt(0)
	v_fma_f32 v26, v28, v26, v29
	s_cmp_eq_u32 s99, 2
	s_cbranch_scc0 .Lcf_skip_2_0
	s_add_u32 s100, s68, 0x162aec40
	s_addc_u32 s101, s69, 0
	global_store_dword v21, v26, s[100:101]

.Lcf_var_3:
	s_add_u32 s100, s68, 0x1612ac40
	s_addc_u32 s101, s69, 0
	global_load_dwordx2 v[48:49], v20, s[100:101] sc1
	s_add_u32 s100, s68, 0x1612cc40
	s_addc_u32 s101, s69, 0
	global_load_dwordx2 v[50:51], v20, s[100:101] sc1
	s_add_u32 s100, s68, 0x1612ec40
	s_addc_u32 s101, s69, 0
	global_load_dwordx2 v[52:53], v20, s[100:101] sc1
	s_add_u32 s100, s68, 0x16130c40
	s_addc_u32 s101, s69, 0
	global_load_dwordx2 v[54:55], v20, s[100:101] sc1
	s_add_u32 s100, s68, 0x16132c40
	s_addc_u32 s101, s69, 0
	global_load_dwordx2 v[56:57], v20, s[100:101] sc1
	s_add_u32 s100, s68, 0x16134c40
	s_addc_u32 s101, s69, 0
	global_load_dwordx2 v[58:59], v20, s[100:101] sc1
	s_add_u32 s100, s68, 0x16136c40
	s_addc_u32 s101, s69, 0
	global_load_dwordx2 v[60:61], v20, s[100:101] sc1
	s_add_u32 s100, s68, 0x16138c40
	s_addc_u32 s101, s69, 0
	global_load_dwordx2 v[62:63], v20, s[100:101] sc1
	s_add_u32 s100, s68, 0x1613ac40
	s_addc_u32 s101, s69, 0
	global_load_dwordx2 v[64:65], v20, s[100:101] sc1
	s_add_u32 s100, s68, 0x1613cc40
	s_addc_u32 s101, s69, 0
	global_load_dwordx2 v[66:67], v20, s[100:101] sc1
	s_add_u32 s100, s68, 0x1613ec40
	s_addc_u32 s101, s69, 0
	global_load_dwordx2 v[68:69], v20, s[100:101] sc1
	s_add_u32 s100, s68, 0x16140c40
	s_addc_u32 s101, s69, 0
	global_load_dwordx2 v[70:71], v20, s[100:101] sc1
	s_add_u32 s100, s68, 0x16142c40
	s_addc_u32 s101, s69, 0
	global_load_dwordx2 v[78:79], v20, s[100:101] sc1
	s_add_u32 s100, s68, 0x16144c40
	s_addc_u32 s101, s69, 0
	global_load_dwordx2 v[80:81], v20, s[100:101] sc1
	s_add_u32 s100, s68, 0x16146c40
	s_addc_u32 s101, s69, 0
	global_load_dwordx2 v[82:83], v20, s[100:101] sc1
	s_add_u32 s100, s68, 0x16148c40
	s_addc_u32 s101, s69, 0
	global_load_dwordx2 v[84:85], v20, s[100:101] sc1
	s_add_u32 s100, s68, 0x1614ac40
	s_addc_u32 s101, s69, 0
	global_load_dwordx2 v[86:87], v20, s[100:101] sc1
	s_add_u32 s100, s68, 0x1614cc40
	s_addc_u32 s101, s69, 0
	global_load_dwordx2 v[88:89], v20, s[100:101] sc1
	s_add_u32 s100, s68, 0x1614ec40
	s_addc_u32 s101, s69, 0
	global_load_dwordx2 v[90:91], v20, s[100:101] sc1
	s_add_u32 s100, s68, 0x16150c40
	s_addc_u32 s101, s69, 0
	global_load_dwordx2 v[92:93], v20, s[100:101] sc1
	s_add_u32 s100, s68, 0x16152c40
	s_addc_u32 s101, s69, 0
	global_load_dwordx2 v[94:95], v20, s[100:101] sc1
	s_add_u32 s100, s68, 0x16154c40
	s_addc_u32 s101, s69, 0
	global_load_dwordx2 v[96:97], v20, s[100:101] sc1
	s_add_u32 s100, s68, 0x16156c40
	s_addc_u32 s101, s69, 0
	global_load_dwordx2 v[98:99], v20, s[100:101] sc1
	s_add_u32 s100, s68, 0x16158c40
	s_addc_u32 s101, s69, 0
	global_load_dwordx2 v[100:101], v20, s[100:101] sc1
	s_add_u32 s100, s68, 0x1615ac40
	s_addc_u32 s101, s69, 0
	global_load_dwordx2 v[102:103], v20, s[100:101] sc1
	s_add_u32 s100, s68, 0x1615cc40
	s_addc_u32 s101, s69, 0
	global_load_dwordx2 v[104:105], v20, s[100:101] sc1
	s_add_u32 s100, s68, 0x1615ec40
	s_addc_u32 s101, s69, 0
	global_load_dwordx2 v[106:107], v20, s[100:101] sc1
	s_add_u32 s100, s68, 0x16160c40
	s_addc_u32 s101, s69, 0
	global_load_dwordx2 v[108:109], v20, s[100:101] sc1
	s_add_u32 s100, s68, 0x16162c40
	s_addc_u32 s101, s69, 0
	global_load_dwordx2 v[110:111], v20, s[100:101] sc1
	s_add_u32 s100, s68, 0x16164c40
	s_addc_u32 s101, s69, 0
	global_load_dwordx2 v[112:113], v20, s[100:101] sc1
	s_add_u32 s100, s68, 0x16166c40
	s_addc_u32 s101, s69, 0
	global_load_dwordx2 v[114:115], v20, s[100:101] sc1
	v_mov_b32_e32 v24, 1.0
	v_mov_b32_e32 v25, 0
	s_waitcnt vmcnt(30)
	v_fma_f32 v25, v48, v25, v49
	v_mul_f32_e32 v24, v24, v48
	s_waitcnt vmcnt(29)
	v_fma_f32 v25, v50, v25, v51
	v_mul_f32_e32 v24, v24, v50
	s_waitcnt vmcnt(28)
	v_fma_f32 v25, v52, v25, v53
	v_mul_f32_e32 v24, v24, v52
	s_waitcnt vmcnt(27)
	v_fma_f32 v25, v54, v25, v55
	v_mul_f32_e32 v24, v24, v54
	s_waitcnt vmcnt(26)
	v_fma_f32 v25, v56, v25, v57
	v_mul_f32_e32 v24, v24, v56
	s_waitcnt vmcnt(25)
	v_fma_f32 v25, v58, v25, v59
	v_mul_f32_e32 v24, v24, v58
	s_waitcnt vmcnt(24)
	v_fma_f32 v25, v60, v25, v61
	v_mul_f32_e32 v24, v24, v60
	s_waitcnt vmcnt(23)
	v_fma_f32 v25, v62, v25, v63
	v_mul_f32_e32 v24, v24, v62
	s_waitcnt vmcnt(22)
	v_fma_f32 v25, v64, v25, v65
	v_mul_f32_e32 v24, v24, v64
	s_waitcnt vmcnt(21)
	v_fma_f32 v25, v66, v25, v67
	v_mul_f32_e32 v24, v24, v66
	s_waitcnt vmcnt(20)
	v_fma_f32 v25, v68, v25, v69
	v_mul_f32_e32 v24, v24, v68
	s_waitcnt vmcnt(19)
	v_fma_f32 v25, v70, v25, v71
	v_mul_f32_e32 v24, v24, v70
	s_waitcnt vmcnt(18)
	v_fma_f32 v25, v78, v25, v79
	v_mul_f32_e32 v24, v24, v78
	s_waitcnt vmcnt(17)
	v_fma_f32 v25, v80, v25, v81
	v_mul_f32_e32 v24, v24, v80
	s_waitcnt vmcnt(16)
	v_fma_f32 v25, v82, v25, v83
	v_mul_f32_e32 v24, v24, v82
	s_waitcnt vmcnt(15)
	v_fma_f32 v25, v84, v25, v85
	v_mul_f32_e32 v24, v24, v84
	s_waitcnt vmcnt(14)
	v_fma_f32 v25, v86, v25, v87
	v_mul_f32_e32 v24, v24, v86
	s_waitcnt vmcnt(13)
	v_fma_f32 v25, v88, v25, v89
	v_mul_f32_e32 v24, v24, v88
	s_waitcnt vmcnt(12)
	v_fma_f32 v25, v90, v25, v91
	v_mul_f32_e32 v24, v24, v90
	s_waitcnt vmcnt(11)
	v_fma_f32 v25, v92, v25, v93
	v_mul_f32_e32 v24, v24, v92
	s_waitcnt vmcnt(10)
	v_fma_f32 v25, v94, v25, v95
	v_mul_f32_e32 v24, v24, v94
	s_waitcnt vmcnt(9)
	v_fma_f32 v25, v96, v25, v97
	v_mul_f32_e32 v24, v24, v96
	s_waitcnt vmcnt(8)
	v_fma_f32 v25, v98, v25, v99
	v_mul_f32_e32 v24, v24, v98
	s_waitcnt vmcnt(7)
	v_fma_f32 v25, v100, v25, v101
	v_mul_f32_e32 v24, v24, v100
	s_waitcnt vmcnt(6)
	v_fma_f32 v25, v102, v25, v103
	v_mul_f32_e32 v24, v24, v102
	s_waitcnt vmcnt(5)
	v_fma_f32 v25, v104, v25, v105
	v_mul_f32_e32 v24, v24, v104
	s_waitcnt vmcnt(4)
	v_fma_f32 v25, v106, v25, v107
	v_mul_f32_e32 v24, v24, v106
	s_waitcnt vmcnt(3)
	v_fma_f32 v25, v108, v25, v109
	v_mul_f32_e32 v24, v24, v108
	s_waitcnt vmcnt(2)
	v_fma_f32 v25, v110, v25, v111
	v_mul_f32_e32 v24, v24, v110
	s_waitcnt vmcnt(1)
	v_fma_f32 v25, v112, v25, v113
	v_mul_f32_e32 v24, v24, v112
	s_waitcnt vmcnt(0)
	v_fma_f32 v25, v114, v25, v115
	v_mul_f32_e32 v24, v24, v114
	ds_write_b64 v22, v[24:25] offset:1536
	s_waitcnt lgkmcnt(0)
	s_barrier
	v_mov_b32_e32 v26, 0
	ds_read_b64 v[28:29], v22 offset:0
	s_waitcnt lgkmcnt(0)
	v_fma_f32 v26, v28, v26, v29
	ds_read_b64 v[28:29], v22 offset:512
	s_waitcnt lgkmcnt(0)
	v_fma_f32 v26, v28, v26, v29
	ds_read_b64 v[28:29], v22 offset:1024
	s_waitcnt lgkmcnt(0)
	v_fma_f32 v26, v28, v26, v29
	s_cmp_eq_u32 s99, 3
	s_cbranch_scc0 .Lcf_skip_3_0
	s_add_u32 s100, s68, 0x162cfc40
	s_addc_u32 s101, s69, 0
	global_store_dword v21, v26, s[100:101]

.Lcf_var_4:
	s_add_u32 s100, s68, 0x1616ac40
	s_addc_u32 s101, s69, 0
	global_load_dwordx2 v[48:49], v20, s[100:101] sc1
	s_add_u32 s100, s68, 0x16168c40
	s_addc_u32 s101, s69, 0
	global_load_dwordx2 v[50:51], v20, s[100:101] sc1
	s_add_u32 s100, s68, 0x1626ac40
	s_addc_u32 s101, s69, 0
	global_load_dwordx2 v[52:53], v20, s[100:101] sc1
	s_add_u32 s100, s68, 0x16268c40
	s_addc_u32 s101, s69, 0
	global_load_dwordx2 v[54:55], v20, s[100:101] sc1
	s_add_u32 s100, s68, 0x16266c40
	s_addc_u32 s101, s69, 0
	global_load_dwordx2 v[56:57], v20, s[100:101] sc1
	s_add_u32 s100, s68, 0x16264c40
	s_addc_u32 s101, s69, 0
	global_load_dwordx2 v[58:59], v20, s[100:101] sc1
	s_add_u32 s100, s68, 0x16262c40
	s_addc_u32 s101, s69, 0
	global_load_dwordx2 v[60:61], v20, s[100:101] sc1
	s_add_u32 s100, s68, 0x16260c40
	s_addc_u32 s101, s69, 0
	global_load_dwordx2 v[62:63], v20, s[100:101] sc1
	s_add_u32 s100, s68, 0x1625ec40
	s_addc_u32 s101, s69, 0
	global_load_dwordx2 v[64:65], v20, s[100:101] sc1
	s_add_u32 s100, s68, 0x1625cc40
	s_addc_u32 s101, s69, 0
	global_load_dwordx2 v[66:67], v20, s[100:101] sc1
	s_add_u32 s100, s68, 0x1625ac40
	s_addc_u32 s101, s69, 0
	global_load_dwordx2 v[68:69], v20, s[100:101] sc1
	s_add_u32 s100, s68, 0x16258c40
	s_addc_u32 s101, s69, 0
	global_load_dwordx2 v[70:71], v20, s[100:101] sc1
	s_add_u32 s100, s68, 0x16256c40
	s_addc_u32 s101, s69, 0
	global_load_dwordx2 v[78:79], v20, s[100:101] sc1
	s_add_u32 s100, s68, 0x16254c40
	s_addc_u32 s101, s69, 0
	global_load_dwordx2 v[80:81], v20, s[100:101] sc1
	s_add_u32 s100, s68, 0x16252c40
	s_addc_u32 s101, s69, 0
	global_load_dwordx2 v[82:83], v20, s[100:101] sc1
	s_add_u32 s100, s68, 0x16250c40
	s_addc_u32 s101, s69, 0
	global_load_dwordx2 v[84:85], v20, s[100:101] sc1
	s_add_u32 s100, s68, 0x1624ec40
	s_addc_u32 s101, s69, 0
	global_load_dwordx2 v[86:87], v20, s[100:101] sc1
	s_add_u32 s100, s68, 0x1624cc40
	s_addc_u32 s101, s69, 0
	global_load_dwordx2 v[88:89], v20, s[100:101] sc1
	s_add_u32 s100, s68, 0x1624ac40
	s_addc_u32 s101, s69, 0
	global_load_dwordx2 v[90:91], v20, s[100:101] sc1
	s_add_u32 s100, s68, 0x16248c40
	s_addc_u32 s101, s69, 0
	global_load_dwordx2 v[92:93], v20, s[100:101] sc1
	s_add_u32 s100, s68, 0x16246c40
	s_addc_u32 s101, s69, 0
	global_load_dwordx2 v[94:95], v20, s[100:101] sc1
	s_add_u32 s100, s68, 0x16244c40
	s_addc_u32 s101, s69, 0
	global_load_dwordx2 v[96:97], v20, s[100:101] sc1
	s_add_u32 s100, s68, 0x16242c40
	s_addc_u32 s101, s69, 0
	global_load_dwordx2 v[98:99], v20, s[100:101] sc1
	s_add_u32 s100, s68, 0x16240c40
	s_addc_u32 s101, s69, 0
	global_load_dwordx2 v[100:101], v20, s[100:101] sc1
	s_add_u32 s100, s68, 0x1623ec40
	s_addc_u32 s101, s69, 0
	global_load_dwordx2 v[102:103], v20, s[100:101] sc1
	s_add_u32 s100, s68, 0x1623cc40
	s_addc_u32 s101, s69, 0
	global_load_dwordx2 v[104:105], v20, s[100:101] sc1
	s_add_u32 s100, s68, 0x1623ac40
	s_addc_u32 s101, s69, 0
	global_load_dwordx2 v[106:107], v20, s[100:101] sc1
	s_add_u32 s100, s68, 0x16238c40
	s_addc_u32 s101, s69, 0
	global_load_dwordx2 v[108:109], v20, s[100:101] sc1
	s_add_u32 s100, s68, 0x16236c40
	s_addc_u32 s101, s69, 0
	global_load_dwordx2 v[110:111], v20, s[100:101] sc1
	s_add_u32 s100, s68, 0x16234c40
	s_addc_u32 s101, s69, 0
	global_load_dwordx2 v[112:113], v20, s[100:101] sc1
	s_add_u32 s100, s68, 0x16232c40
	s_addc_u32 s101, s69, 0
	global_load_dwordx2 v[114:115], v20, s[100:101] sc1
	s_add_u32 s100, s68, 0x16230c40
	s_addc_u32 s101, s69, 0
	global_load_dwordx2 v[116:117], v20, s[100:101] sc1
	s_add_u32 s100, s68, 0x1622ec40
	s_addc_u32 s101, s69, 0
	global_load_dwordx2 v[118:119], v20, s[100:101] sc1
	v_mov_b32_e32 v24, 1.0
	v_mov_b32_e32 v25, 0
	s_waitcnt vmcnt(32)
	v_fma_f32 v25, v48, v25, v49
	v_mul_f32_e32 v24, v24, v48
	s_waitcnt vmcnt(31)
	v_fma_f32 v25, v50, v25, v51
	v_mul_f32_e32 v24, v24, v50
	s_waitcnt vmcnt(30)
	v_fma_f32 v25, v52, v25, v53
	v_mul_f32_e32 v24, v24, v52
	s_waitcnt vmcnt(29)
	v_fma_f32 v25, v54, v25, v55
	v_mul_f32_e32 v24, v24, v54
	s_waitcnt vmcnt(28)
	v_fma_f32 v25, v56, v25, v57
	v_mul_f32_e32 v24, v24, v56
	s_waitcnt vmcnt(27)
	v_fma_f32 v25, v58, v25, v59
	v_mul_f32_e32 v24, v24, v58
	s_waitcnt vmcnt(26)
	v_fma_f32 v25, v60, v25, v61
	v_mul_f32_e32 v24, v24, v60
	s_waitcnt vmcnt(25)
	v_fma_f32 v25, v62, v25, v63
	v_mul_f32_e32 v24, v24, v62
	s_waitcnt vmcnt(24)
	v_fma_f32 v25, v64, v25, v65
	v_mul_f32_e32 v24, v24, v64
	s_waitcnt vmcnt(23)
	v_fma_f32 v25, v66, v25, v67
	v_mul_f32_e32 v24, v24, v66
	s_waitcnt vmcnt(22)
	v_fma_f32 v25, v68, v25, v69
	v_mul_f32_e32 v24, v24, v68
	s_waitcnt vmcnt(21)
	v_fma_f32 v25, v70, v25, v71
	v_mul_f32_e32 v24, v24, v70
	s_waitcnt vmcnt(20)
	v_fma_f32 v25, v78, v25, v79
	v_mul_f32_e32 v24, v24, v78
	s_waitcnt vmcnt(19)
	v_fma_f32 v25, v80, v25, v81
	v_mul_f32_e32 v24, v24, v80
	s_waitcnt vmcnt(18)
	v_fma_f32 v25, v82, v25, v83
	v_mul_f32_e32 v24, v24, v82
	s_waitcnt vmcnt(17)
	v_fma_f32 v25, v84, v25, v85
	v_mul_f32_e32 v24, v24, v84
	s_waitcnt vmcnt(16)
	v_fma_f32 v25, v86, v25, v87
	v_mul_f32_e32 v24, v24, v86
	s_waitcnt vmcnt(15)
	v_fma_f32 v25, v88, v25, v89
	v_mul_f32_e32 v24, v24, v88
	s_waitcnt vmcnt(14)
	v_fma_f32 v25, v90, v25, v91
	v_mul_f32_e32 v24, v24, v90
	s_waitcnt vmcnt(13)
	v_fma_f32 v25, v92, v25, v93
	v_mul_f32_e32 v24, v24, v92
	s_waitcnt vmcnt(12)
	v_fma_f32 v25, v94, v25, v95
	v_mul_f32_e32 v24, v24, v94
	s_waitcnt vmcnt(11)
	v_fma_f32 v25, v96, v25, v97
	v_mul_f32_e32 v24, v24, v96
	s_waitcnt vmcnt(10)
	v_fma_f32 v25, v98, v25, v99
	v_mul_f32_e32 v24, v24, v98
	s_waitcnt vmcnt(9)
	v_fma_f32 v25, v100, v25, v101
	v_mul_f32_e32 v24, v24, v100
	s_waitcnt vmcnt(8)
	v_fma_f32 v25, v102, v25, v103
	v_mul_f32_e32 v24, v24, v102
	s_waitcnt vmcnt(7)
	v_fma_f32 v25, v104, v25, v105
	v_mul_f32_e32 v24, v24, v104
	s_waitcnt vmcnt(6)
	v_fma_f32 v25, v106, v25, v107
	v_mul_f32_e32 v24, v24, v106
	s_waitcnt vmcnt(5)
	v_fma_f32 v25, v108, v25, v109
	v_mul_f32_e32 v24, v24, v108
	s_waitcnt vmcnt(4)
	v_fma_f32 v25, v110, v25, v111
	v_mul_f32_e32 v24, v24, v110
	s_waitcnt vmcnt(3)
	v_fma_f32 v25, v112, v25, v113
	v_mul_f32_e32 v24, v24, v112
	s_waitcnt vmcnt(2)
	v_fma_f32 v25, v114, v25, v115
	v_mul_f32_e32 v24, v24, v114
	s_waitcnt vmcnt(1)
	v_fma_f32 v25, v116, v25, v117
	v_mul_f32_e32 v24, v24, v116
	s_waitcnt vmcnt(0)
	v_fma_f32 v25, v118, v25, v119
	v_mul_f32_e32 v24, v24, v118
	ds_write_b64 v22, v[24:25] offset:2048
	s_waitcnt lgkmcnt(0)
	s_barrier
	v_mov_b32_e32 v26, 0
	s_cmp_eq_u32 s99, 1
	s_cbranch_scc0 .Lcf_skip_4_0
	s_add_u32 s100, s68, 0x162efc40
	s_addc_u32 s101, s69, 0
	global_store_dword v21, v26, s[100:101]

.Lcf_var_5:
	s_add_u32 s100, s68, 0x1622cc40
	s_addc_u32 s101, s69, 0
	global_load_dwordx2 v[48:49], v20, s[100:101] sc1
	s_add_u32 s100, s68, 0x1622ac40
	s_addc_u32 s101, s69, 0
	global_load_dwordx2 v[50:51], v20, s[100:101] sc1
	s_add_u32 s100, s68, 0x16228c40
	s_addc_u32 s101, s69, 0
	global_load_dwordx2 v[52:53], v20, s[100:101] sc1
	s_add_u32 s100, s68, 0x16226c40
	s_addc_u32 s101, s69, 0
	global_load_dwordx2 v[54:55], v20, s[100:101] sc1
	s_add_u32 s100, s68, 0x16224c40
	s_addc_u32 s101, s69, 0
	global_load_dwordx2 v[56:57], v20, s[100:101] sc1
	s_add_u32 s100, s68, 0x16222c40
	s_addc_u32 s101, s69, 0
	global_load_dwordx2 v[58:59], v20, s[100:101] sc1
	s_add_u32 s100, s68, 0x16220c40
	s_addc_u32 s101, s69, 0
	global_load_dwordx2 v[60:61], v20, s[100:101] sc1
	s_add_u32 s100, s68, 0x1621ec40
	s_addc_u32 s101, s69, 0
	global_load_dwordx2 v[62:63], v20, s[100:101] sc1
	s_add_u32 s100, s68, 0x1621cc40
	s_addc_u32 s101, s69, 0
	global_load_dwordx2 v[64:65], v20, s[100:101] sc1
	s_add_u32 s100, s68, 0x1621ac40
	s_addc_u32 s101, s69, 0
	global_load_dwordx2 v[66:67], v20, s[100:101] sc1
	s_add_u32 s100, s68, 0x16218c40
	s_addc_u32 s101, s69, 0
	global_load_dwordx2 v[68:69], v20, s[100:101] sc1
	s_add_u32 s100, s68, 0x16216c40
	s_addc_u32 s101, s69, 0
	global_load_dwordx2 v[70:71], v20, s[100:101] sc1
	s_add_u32 s100, s68, 0x16214c40
	s_addc_u32 s101, s69, 0
	global_load_dwordx2 v[78:79], v20, s[100:101] sc1
	s_add_u32 s100, s68, 0x16212c40
	s_addc_u32 s101, s69, 0
	global_load_dwordx2 v[80:81], v20, s[100:101] sc1
	s_add_u32 s100, s68, 0x16210c40
	s_addc_u32 s101, s69, 0
	global_load_dwordx2 v[82:83], v20, s[100:101] sc1
	s_add_u32 s100, s68, 0x1620ec40
	s_addc_u32 s101, s69, 0
	global_load_dwordx2 v[84:85], v20, s[100:101] sc1
	s_add_u32 s100, s68, 0x1620cc40
	s_addc_u32 s101, s69, 0
	global_load_dwordx2 v[86:87], v20, s[100:101] sc1
	s_add_u32 s100, s68, 0x1620ac40
	s_addc_u32 s101, s69, 0
	global_load_dwordx2 v[88:89], v20, s[100:101] sc1
	s_add_u32 s100, s68, 0x16208c40
	s_addc_u32 s101, s69, 0
	global_load_dwordx2 v[90:91], v20, s[100:101] sc1
	s_add_u32 s100, s68, 0x16206c40
	s_addc_u32 s101, s69, 0
	global_load_dwordx2 v[92:93], v20, s[100:101] sc1
	s_add_u32 s100, s68, 0x16204c40
	s_addc_u32 s101, s69, 0
	global_load_dwordx2 v[94:95], v20, s[100:101] sc1
	s_add_u32 s100, s68, 0x16202c40
	s_addc_u32 s101, s69, 0
	global_load_dwordx2 v[96:97], v20, s[100:101] sc1
	s_add_u32 s100, s68, 0x16200c40
	s_addc_u32 s101, s69, 0
	global_load_dwordx2 v[98:99], v20, s[100:101] sc1
	s_add_u32 s100, s68, 0x161fec40
	s_addc_u32 s101, s69, 0
	global_load_dwordx2 v[100:101], v20, s[100:101] sc1
	s_add_u32 s100, s68, 0x161fcc40
	s_addc_u32 s101, s69, 0
	global_load_dwordx2 v[102:103], v20, s[100:101] sc1
	s_add_u32 s100, s68, 0x161fac40
	s_addc_u32 s101, s69, 0
	global_load_dwordx2 v[104:105], v20, s[100:101] sc1
	s_add_u32 s100, s68, 0x161f8c40
	s_addc_u32 s101, s69, 0
	global_load_dwordx2 v[106:107], v20, s[100:101] sc1
	s_add_u32 s100, s68, 0x161f6c40
	s_addc_u32 s101, s69, 0
	global_load_dwordx2 v[108:109], v20, s[100:101] sc1
	s_add_u32 s100, s68, 0x161f4c40
	s_addc_u32 s101, s69, 0
	global_load_dwordx2 v[110:111], v20, s[100:101] sc1
	s_add_u32 s100, s68, 0x161f2c40
	s_addc_u32 s101, s69, 0
	global_load_dwordx2 v[112:113], v20, s[100:101] sc1
	s_add_u32 s100, s68, 0x161f0c40
	s_addc_u32 s101, s69, 0
	global_load_dwordx2 v[114:115], v20, s[100:101] sc1
	s_add_u32 s100, s68, 0x161eec40
	s_addc_u32 s101, s69, 0
	global_load_dwordx2 v[116:117], v20, s[100:101] sc1
	s_add_u32 s100, s68, 0x161ecc40
	s_addc_u32 s101, s69, 0
	global_load_dwordx2 v[118:119], v20, s[100:101] sc1
	v_mov_b32_e32 v24, 1.0
	v_mov_b32_e32 v25, 0
	s_waitcnt vmcnt(32)
	v_fma_f32 v25, v48, v25, v49
	v_mul_f32_e32 v24, v24, v48
	s_waitcnt vmcnt(31)
	v_fma_f32 v25, v50, v25, v51
	v_mul_f32_e32 v24, v24, v50
	s_waitcnt vmcnt(30)
	v_fma_f32 v25, v52, v25, v53
	v_mul_f32_e32 v24, v24, v52
	s_waitcnt vmcnt(29)
	v_fma_f32 v25, v54, v25, v55
	v_mul_f32_e32 v24, v24, v54
	s_waitcnt vmcnt(28)
	v_fma_f32 v25, v56, v25, v57
	v_mul_f32_e32 v24, v24, v56
	s_waitcnt vmcnt(27)
	v_fma_f32 v25, v58, v25, v59
	v_mul_f32_e32 v24, v24, v58
	s_waitcnt vmcnt(26)
	v_fma_f32 v25, v60, v25, v61
	v_mul_f32_e32 v24, v24, v60
	s_waitcnt vmcnt(25)
	v_fma_f32 v25, v62, v25, v63
	v_mul_f32_e32 v24, v24, v62
	s_waitcnt vmcnt(24)
	v_fma_f32 v25, v64, v25, v65
	v_mul_f32_e32 v24, v24, v64
	s_waitcnt vmcnt(23)
	v_fma_f32 v25, v66, v25, v67
	v_mul_f32_e32 v24, v24, v66
	s_waitcnt vmcnt(22)
	v_fma_f32 v25, v68, v25, v69
	v_mul_f32_e32 v24, v24, v68
	s_waitcnt vmcnt(21)
	v_fma_f32 v25, v70, v25, v71
	v_mul_f32_e32 v24, v24, v70
	s_waitcnt vmcnt(20)
	v_fma_f32 v25, v78, v25, v79
	v_mul_f32_e32 v24, v24, v78
	s_waitcnt vmcnt(19)
	v_fma_f32 v25, v80, v25, v81
	v_mul_f32_e32 v24, v24, v80
	s_waitcnt vmcnt(18)
	v_fma_f32 v25, v82, v25, v83
	v_mul_f32_e32 v24, v24, v82
	s_waitcnt vmcnt(17)
	v_fma_f32 v25, v84, v25, v85
	v_mul_f32_e32 v24, v24, v84
	s_waitcnt vmcnt(16)
	v_fma_f32 v25, v86, v25, v87
	v_mul_f32_e32 v24, v24, v86
	s_waitcnt vmcnt(15)
	v_fma_f32 v25, v88, v25, v89
	v_mul_f32_e32 v24, v24, v88
	s_waitcnt vmcnt(14)
	v_fma_f32 v25, v90, v25, v91
	v_mul_f32_e32 v24, v24, v90
	s_waitcnt vmcnt(13)
	v_fma_f32 v25, v92, v25, v93
	v_mul_f32_e32 v24, v24, v92
	s_waitcnt vmcnt(12)
	v_fma_f32 v25, v94, v25, v95
	v_mul_f32_e32 v24, v24, v94
	s_waitcnt vmcnt(11)
	v_fma_f32 v25, v96, v25, v97
	v_mul_f32_e32 v24, v24, v96
	s_waitcnt vmcnt(10)
	v_fma_f32 v25, v98, v25, v99
	v_mul_f32_e32 v24, v24, v98
	s_waitcnt vmcnt(9)
	v_fma_f32 v25, v100, v25, v101
	v_mul_f32_e32 v24, v24, v100
	s_waitcnt vmcnt(8)
	v_fma_f32 v25, v102, v25, v103
	v_mul_f32_e32 v24, v24, v102
	s_waitcnt vmcnt(7)
	v_fma_f32 v25, v104, v25, v105
	v_mul_f32_e32 v24, v24, v104
	s_waitcnt vmcnt(6)
	v_fma_f32 v25, v106, v25, v107
	v_mul_f32_e32 v24, v24, v106
	s_waitcnt vmcnt(5)
	v_fma_f32 v25, v108, v25, v109
	v_mul_f32_e32 v24, v24, v108
	s_waitcnt vmcnt(4)
	v_fma_f32 v25, v110, v25, v111
	v_mul_f32_e32 v24, v24, v110
	s_waitcnt vmcnt(3)
	v_fma_f32 v25, v112, v25, v113
	v_mul_f32_e32 v24, v24, v112
	s_waitcnt vmcnt(2)
	v_fma_f32 v25, v114, v25, v115
	v_mul_f32_e32 v24, v24, v114
	s_waitcnt vmcnt(1)
	v_fma_f32 v25, v116, v25, v117
	v_mul_f32_e32 v24, v24, v116
	s_waitcnt vmcnt(0)
	v_fma_f32 v25, v118, v25, v119
	v_mul_f32_e32 v24, v24, v118
	ds_write_b64 v22, v[24:25] offset:2560
	s_waitcnt lgkmcnt(0)
	s_barrier
	v_mov_b32_e32 v26, 0
	ds_read_b64 v[28:29], v22 offset:2048
	s_waitcnt lgkmcnt(0)
	v_fma_f32 v26, v28, v26, v29
	s_cmp_eq_u32 s99, 2
	s_cbranch_scc0 .Lcf_skip_5_0
	s_add_u32 s100, s68, 0x16350c40
	s_addc_u32 s101, s69, 0
	global_store_dword v21, v26, s[100:101]

.Lcf_var_6:
	s_add_u32 s100, s68, 0x161eac40
	s_addc_u32 s101, s69, 0
	global_load_dwordx2 v[48:49], v20, s[100:101] sc1
	s_add_u32 s100, s68, 0x161e8c40
	s_addc_u32 s101, s69, 0
	global_load_dwordx2 v[50:51], v20, s[100:101] sc1
	s_add_u32 s100, s68, 0x161e6c40
	s_addc_u32 s101, s69, 0
	global_load_dwordx2 v[52:53], v20, s[100:101] sc1
	s_add_u32 s100, s68, 0x161e4c40
	s_addc_u32 s101, s69, 0
	global_load_dwordx2 v[54:55], v20, s[100:101] sc1
	s_add_u32 s100, s68, 0x161e2c40
	s_addc_u32 s101, s69, 0
	global_load_dwordx2 v[56:57], v20, s[100:101] sc1
	s_add_u32 s100, s68, 0x161e0c40
	s_addc_u32 s101, s69, 0
	global_load_dwordx2 v[58:59], v20, s[100:101] sc1
	s_add_u32 s100, s68, 0x161dec40
	s_addc_u32 s101, s69, 0
	global_load_dwordx2 v[60:61], v20, s[100:101] sc1
	s_add_u32 s100, s68, 0x161dcc40
	s_addc_u32 s101, s69, 0
	global_load_dwordx2 v[62:63], v20, s[100:101] sc1
	s_add_u32 s100, s68, 0x161dac40
	s_addc_u32 s101, s69, 0
	global_load_dwordx2 v[64:65], v20, s[100:101] sc1
	s_add_u32 s100, s68, 0x161d8c40
	s_addc_u32 s101, s69, 0
	global_load_dwordx2 v[66:67], v20, s[100:101] sc1
	s_add_u32 s100, s68, 0x161d6c40
	s_addc_u32 s101, s69, 0
	global_load_dwordx2 v[68:69], v20, s[100:101] sc1
	s_add_u32 s100, s68, 0x161d4c40
	s_addc_u32 s101, s69, 0
	global_load_dwordx2 v[70:71], v20, s[100:101] sc1
	s_add_u32 s100, s68, 0x161d2c40
	s_addc_u32 s101, s69, 0
	global_load_dwordx2 v[78:79], v20, s[100:101] sc1
	s_add_u32 s100, s68, 0x161d0c40
	s_addc_u32 s101, s69, 0
	global_load_dwordx2 v[80:81], v20, s[100:101] sc1
	s_add_u32 s100, s68, 0x161cec40
	s_addc_u32 s101, s69, 0
	global_load_dwordx2 v[82:83], v20, s[100:101] sc1
	s_add_u32 s100, s68, 0x161ccc40
	s_addc_u32 s101, s69, 0
	global_load_dwordx2 v[84:85], v20, s[100:101] sc1
	s_add_u32 s100, s68, 0x161cac40
	s_addc_u32 s101, s69, 0
	global_load_dwordx2 v[86:87], v20, s[100:101] sc1
	s_add_u32 s100, s68, 0x161c8c40
	s_addc_u32 s101, s69, 0
	global_load_dwordx2 v[88:89], v20, s[100:101] sc1
	s_add_u32 s100, s68, 0x161c6c40
	s_addc_u32 s101, s69, 0
	global_load_dwordx2 v[90:91], v20, s[100:101] sc1
	s_add_u32 s100, s68, 0x161c4c40
	s_addc_u32 s101, s69, 0
	global_load_dwordx2 v[92:93], v20, s[100:101] sc1
	s_add_u32 s100, s68, 0x161c2c40
	s_addc_u32 s101, s69, 0
	global_load_dwordx2 v[94:95], v20, s[100:101] sc1
	s_add_u32 s100, s68, 0x161c0c40
	s_addc_u32 s101, s69, 0
	global_load_dwordx2 v[96:97], v20, s[100:101] sc1
	s_add_u32 s100, s68, 0x161bec40
	s_addc_u32 s101, s69, 0
	global_load_dwordx2 v[98:99], v20, s[100:101] sc1
	s_add_u32 s100, s68, 0x161bcc40
	s_addc_u32 s101, s69, 0
	global_load_dwordx2 v[100:101], v20, s[100:101] sc1
	s_add_u32 s100, s68, 0x161bac40
	s_addc_u32 s101, s69, 0
	global_load_dwordx2 v[102:103], v20, s[100:101] sc1
	s_add_u32 s100, s68, 0x161b8c40
	s_addc_u32 s101, s69, 0
	global_load_dwordx2 v[104:105], v20, s[100:101] sc1
	s_add_u32 s100, s68, 0x161b6c40
	s_addc_u32 s101, s69, 0
	global_load_dwordx2 v[106:107], v20, s[100:101] sc1
	s_add_u32 s100, s68, 0x161b4c40
	s_addc_u32 s101, s69, 0
	global_load_dwordx2 v[108:109], v20, s[100:101] sc1
	s_add_u32 s100, s68, 0x161b2c40
	s_addc_u32 s101, s69, 0
	global_load_dwordx2 v[110:111], v20, s[100:101] sc1
	s_add_u32 s100, s68, 0x161b0c40
	s_addc_u32 s101, s69, 0
	global_load_dwordx2 v[112:113], v20, s[100:101] sc1
	s_add_u32 s100, s68, 0x161aec40
	s_addc_u32 s101, s69, 0
	global_load_dwordx2 v[114:115], v20, s[100:101] sc1
	s_add_u32 s100, s68, 0x161acc40
	s_addc_u32 s101, s69, 0
	global_load_dwordx2 v[116:117], v20, s[100:101] sc1
	s_add_u32 s100, s68, 0x161aac40
	s_addc_u32 s101, s69, 0
	global_load_dwordx2 v[118:119], v20, s[100:101] sc1
	v_mov_b32_e32 v24, 1.0
	v_mov_b32_e32 v25, 0
	s_waitcnt vmcnt(32)
	v_fma_f32 v25, v48, v25, v49
	v_mul_f32_e32 v24, v24, v48
	s_waitcnt vmcnt(31)
	v_fma_f32 v25, v50, v25, v51
	v_mul_f32_e32 v24, v24, v50
	s_waitcnt vmcnt(30)
	v_fma_f32 v25, v52, v25, v53
	v_mul_f32_e32 v24, v24, v52
	s_waitcnt vmcnt(29)
	v_fma_f32 v25, v54, v25, v55
	v_mul_f32_e32 v24, v24, v54
	s_waitcnt vmcnt(28)
	v_fma_f32 v25, v56, v25, v57
	v_mul_f32_e32 v24, v24, v56
	s_waitcnt vmcnt(27)
	v_fma_f32 v25, v58, v25, v59
	v_mul_f32_e32 v24, v24, v58
	s_waitcnt vmcnt(26)
	v_fma_f32 v25, v60, v25, v61
	v_mul_f32_e32 v24, v24, v60
	s_waitcnt vmcnt(25)
	v_fma_f32 v25, v62, v25, v63
	v_mul_f32_e32 v24, v24, v62
	s_waitcnt vmcnt(24)
	v_fma_f32 v25, v64, v25, v65
	v_mul_f32_e32 v24, v24, v64
	s_waitcnt vmcnt(23)
	v_fma_f32 v25, v66, v25, v67
	v_mul_f32_e32 v24, v24, v66
	s_waitcnt vmcnt(22)
	v_fma_f32 v25, v68, v25, v69
	v_mul_f32_e32 v24, v24, v68
	s_waitcnt vmcnt(21)
	v_fma_f32 v25, v70, v25, v71
	v_mul_f32_e32 v24, v24, v70
	s_waitcnt vmcnt(20)
	v_fma_f32 v25, v78, v25, v79
	v_mul_f32_e32 v24, v24, v78
	s_waitcnt vmcnt(19)
	v_fma_f32 v25, v80, v25, v81
	v_mul_f32_e32 v24, v24, v80
	s_waitcnt vmcnt(18)
	v_fma_f32 v25, v82, v25, v83
	v_mul_f32_e32 v24, v24, v82
	s_waitcnt vmcnt(17)
	v_fma_f32 v25, v84, v25, v85
	v_mul_f32_e32 v24, v24, v84
	s_waitcnt vmcnt(16)
	v_fma_f32 v25, v86, v25, v87
	v_mul_f32_e32 v24, v24, v86
	s_waitcnt vmcnt(15)
	v_fma_f32 v25, v88, v25, v89
	v_mul_f32_e32 v24, v24, v88
	s_waitcnt vmcnt(14)
	v_fma_f32 v25, v90, v25, v91
	v_mul_f32_e32 v24, v24, v90
	s_waitcnt vmcnt(13)
	v_fma_f32 v25, v92, v25, v93
	v_mul_f32_e32 v24, v24, v92
	s_waitcnt vmcnt(12)
	v_fma_f32 v25, v94, v25, v95
	v_mul_f32_e32 v24, v24, v94
	s_waitcnt vmcnt(11)
	v_fma_f32 v25, v96, v25, v97
	v_mul_f32_e32 v24, v24, v96
	s_waitcnt vmcnt(10)
	v_fma_f32 v25, v98, v25, v99
	v_mul_f32_e32 v24, v24, v98
	s_waitcnt vmcnt(9)
	v_fma_f32 v25, v100, v25, v101
	v_mul_f32_e32 v24, v24, v100
	s_waitcnt vmcnt(8)
	v_fma_f32 v25, v102, v25, v103
	v_mul_f32_e32 v24, v24, v102
	s_waitcnt vmcnt(7)
	v_fma_f32 v25, v104, v25, v105
	v_mul_f32_e32 v24, v24, v104
	s_waitcnt vmcnt(6)
	v_fma_f32 v25, v106, v25, v107
	v_mul_f32_e32 v24, v24, v106
	s_waitcnt vmcnt(5)
	v_fma_f32 v25, v108, v25, v109
	v_mul_f32_e32 v24, v24, v108
	s_waitcnt vmcnt(4)
	v_fma_f32 v25, v110, v25, v111
	v_mul_f32_e32 v24, v24, v110
	s_waitcnt vmcnt(3)
	v_fma_f32 v25, v112, v25, v113
	v_mul_f32_e32 v24, v24, v112
	s_waitcnt vmcnt(2)
	v_fma_f32 v25, v114, v25, v115
	v_mul_f32_e32 v24, v24, v114
	s_waitcnt vmcnt(1)
	v_fma_f32 v25, v116, v25, v117
	v_mul_f32_e32 v24, v24, v116
	s_waitcnt vmcnt(0)
	v_fma_f32 v25, v118, v25, v119
	v_mul_f32_e32 v24, v24, v118
	ds_write_b64 v22, v[24:25] offset:3072
	s_waitcnt lgkmcnt(0)
	s_barrier
	v_mov_b32_e32 v26, 0
	ds_read_b64 v[28:29], v22 offset:2048
	s_waitcnt lgkmcnt(0)
	v_fma_f32 v26, v28, v26, v29
	ds_read_b64 v[28:29], v22 offset:2560
	s_waitcnt lgkmcnt(0)
	v_fma_f32 v26, v28, v26, v29
	s_cmp_eq_u32 s99, 1
	s_cbranch_scc0 .Lcf_skip_6_0
	s_add_u32 s100, s68, 0x1632fc40
	s_addc_u32 s101, s69, 0
	global_store_dword v21, v26, s[100:101]

.Lcf_var_7:
	s_add_u32 s100, s68, 0x161a8c40
	s_addc_u32 s101, s69, 0
	global_load_dwordx2 v[48:49], v20, s[100:101] sc1
	s_add_u32 s100, s68, 0x161a6c40
	s_addc_u32 s101, s69, 0
	global_load_dwordx2 v[50:51], v20, s[100:101] sc1
	s_add_u32 s100, s68, 0x161a4c40
	s_addc_u32 s101, s69, 0
	global_load_dwordx2 v[52:53], v20, s[100:101] sc1
	s_add_u32 s100, s68, 0x161a2c40
	s_addc_u32 s101, s69, 0
	global_load_dwordx2 v[54:55], v20, s[100:101] sc1
	s_add_u32 s100, s68, 0x161a0c40
	s_addc_u32 s101, s69, 0
	global_load_dwordx2 v[56:57], v20, s[100:101] sc1
	s_add_u32 s100, s68, 0x1619ec40
	s_addc_u32 s101, s69, 0
	global_load_dwordx2 v[58:59], v20, s[100:101] sc1
	s_add_u32 s100, s68, 0x1619cc40
	s_addc_u32 s101, s69, 0
	global_load_dwordx2 v[60:61], v20, s[100:101] sc1
	s_add_u32 s100, s68, 0x1619ac40
	s_addc_u32 s101, s69, 0
	global_load_dwordx2 v[62:63], v20, s[100:101] sc1
	s_add_u32 s100, s68, 0x16198c40
	s_addc_u32 s101, s69, 0
	global_load_dwordx2 v[64:65], v20, s[100:101] sc1
	s_add_u32 s100, s68, 0x16196c40
	s_addc_u32 s101, s69, 0
	global_load_dwordx2 v[66:67], v20, s[100:101] sc1
	s_add_u32 s100, s68, 0x16194c40
	s_addc_u32 s101, s69, 0
	global_load_dwordx2 v[68:69], v20, s[100:101] sc1
	s_add_u32 s100, s68, 0x16192c40
	s_addc_u32 s101, s69, 0
	global_load_dwordx2 v[70:71], v20, s[100:101] sc1
	s_add_u32 s100, s68, 0x16190c40
	s_addc_u32 s101, s69, 0
	global_load_dwordx2 v[78:79], v20, s[100:101] sc1
	s_add_u32 s100, s68, 0x1618ec40
	s_addc_u32 s101, s69, 0
	global_load_dwordx2 v[80:81], v20, s[100:101] sc1
	s_add_u32 s100, s68, 0x1618cc40
	s_addc_u32 s101, s69, 0
	global_load_dwordx2 v[82:83], v20, s[100:101] sc1
	s_add_u32 s100, s68, 0x1618ac40
	s_addc_u32 s101, s69, 0
	global_load_dwordx2 v[84:85], v20, s[100:101] sc1
	s_add_u32 s100, s68, 0x16188c40
	s_addc_u32 s101, s69, 0
	global_load_dwordx2 v[86:87], v20, s[100:101] sc1
	s_add_u32 s100, s68, 0x16186c40
	s_addc_u32 s101, s69, 0
	global_load_dwordx2 v[88:89], v20, s[100:101] sc1
	s_add_u32 s100, s68, 0x16184c40
	s_addc_u32 s101, s69, 0
	global_load_dwordx2 v[90:91], v20, s[100:101] sc1
	s_add_u32 s100, s68, 0x16182c40
	s_addc_u32 s101, s69, 0
	global_load_dwordx2 v[92:93], v20, s[100:101] sc1
	s_add_u32 s100, s68, 0x16180c40
	s_addc_u32 s101, s69, 0
	global_load_dwordx2 v[94:95], v20, s[100:101] sc1
	s_add_u32 s100, s68, 0x1617ec40
	s_addc_u32 s101, s69, 0
	global_load_dwordx2 v[96:97], v20, s[100:101] sc1
	s_add_u32 s100, s68, 0x1617cc40
	s_addc_u32 s101, s69, 0
	global_load_dwordx2 v[98:99], v20, s[100:101] sc1
	s_add_u32 s100, s68, 0x1617ac40
	s_addc_u32 s101, s69, 0
	global_load_dwordx2 v[100:101], v20, s[100:101] sc1
	s_add_u32 s100, s68, 0x16178c40
	s_addc_u32 s101, s69, 0
	global_load_dwordx2 v[102:103], v20, s[100:101] sc1
	s_add_u32 s100, s68, 0x16176c40
	s_addc_u32 s101, s69, 0
	global_load_dwordx2 v[104:105], v20, s[100:101] sc1
	s_add_u32 s100, s68, 0x16174c40
	s_addc_u32 s101, s69, 0
	global_load_dwordx2 v[106:107], v20, s[100:101] sc1
	s_add_u32 s100, s68, 0x16172c40
	s_addc_u32 s101, s69, 0
	global_load_dwordx2 v[108:109], v20, s[100:101] sc1
	s_add_u32 s100, s68, 0x16170c40
	s_addc_u32 s101, s69, 0
	global_load_dwordx2 v[110:111], v20, s[100:101] sc1
	s_add_u32 s100, s68, 0x1616ec40
	s_addc_u32 s101, s69, 0
	global_load_dwordx2 v[112:113], v20, s[100:101] sc1
	s_add_u32 s100, s68, 0x1616cc40
	s_addc_u32 s101, s69, 0
	global_load_dwordx2 v[114:115], v20, s[100:101] sc1
	v_mov_b32_e32 v24, 1.0
	v_mov_b32_e32 v25, 0
	s_waitcnt vmcnt(30)
	v_fma_f32 v25, v48, v25, v49
	v_mul_f32_e32 v24, v24, v48
	s_waitcnt vmcnt(29)
	v_fma_f32 v25, v50, v25, v51
	v_mul_f32_e32 v24, v24, v50
	s_waitcnt vmcnt(28)
	v_fma_f32 v25, v52, v25, v53
	v_mul_f32_e32 v24, v24, v52
	s_waitcnt vmcnt(27)
	v_fma_f32 v25, v54, v25, v55
	v_mul_f32_e32 v24, v24, v54
	s_waitcnt vmcnt(26)
	v_fma_f32 v25, v56, v25, v57
	v_mul_f32_e32 v24, v24, v56
	s_waitcnt vmcnt(25)
	v_fma_f32 v25, v58, v25, v59
	v_mul_f32_e32 v24, v24, v58
	s_waitcnt vmcnt(24)
	v_fma_f32 v25, v60, v25, v61
	v_mul_f32_e32 v24, v24, v60
	s_waitcnt vmcnt(23)
	v_fma_f32 v25, v62, v25, v63
	v_mul_f32_e32 v24, v24, v62
	s_waitcnt vmcnt(22)
	v_fma_f32 v25, v64, v25, v65
	v_mul_f32_e32 v24, v24, v64
	s_waitcnt vmcnt(21)
	v_fma_f32 v25, v66, v25, v67
	v_mul_f32_e32 v24, v24, v66
	s_waitcnt vmcnt(20)
	v_fma_f32 v25, v68, v25, v69
	v_mul_f32_e32 v24, v24, v68
	s_waitcnt vmcnt(19)
	v_fma_f32 v25, v70, v25, v71
	v_mul_f32_e32 v24, v24, v70
	s_waitcnt vmcnt(18)
	v_fma_f32 v25, v78, v25, v79
	v_mul_f32_e32 v24, v24, v78
	s_waitcnt vmcnt(17)
	v_fma_f32 v25, v80, v25, v81
	v_mul_f32_e32 v24, v24, v80
	s_waitcnt vmcnt(16)
	v_fma_f32 v25, v82, v25, v83
	v_mul_f32_e32 v24, v24, v82
	s_waitcnt vmcnt(15)
	v_fma_f32 v25, v84, v25, v85
	v_mul_f32_e32 v24, v24, v84
	s_waitcnt vmcnt(14)
	v_fma_f32 v25, v86, v25, v87
	v_mul_f32_e32 v24, v24, v86
	s_waitcnt vmcnt(13)
	v_fma_f32 v25, v88, v25, v89
	v_mul_f32_e32 v24, v24, v88
	s_waitcnt vmcnt(12)
	v_fma_f32 v25, v90, v25, v91
	v_mul_f32_e32 v24, v24, v90
	s_waitcnt vmcnt(11)
	v_fma_f32 v25, v92, v25, v93
	v_mul_f32_e32 v24, v24, v92
	s_waitcnt vmcnt(10)
	v_fma_f32 v25, v94, v25, v95
	v_mul_f32_e32 v24, v24, v94
	s_waitcnt vmcnt(9)
	v_fma_f32 v25, v96, v25, v97
	v_mul_f32_e32 v24, v24, v96
	s_waitcnt vmcnt(8)
	v_fma_f32 v25, v98, v25, v99
	v_mul_f32_e32 v24, v24, v98
	s_waitcnt vmcnt(7)
	v_fma_f32 v25, v100, v25, v101
	v_mul_f32_e32 v24, v24, v100
	s_waitcnt vmcnt(6)
	v_fma_f32 v25, v102, v25, v103
	v_mul_f32_e32 v24, v24, v102
	s_waitcnt vmcnt(5)
	v_fma_f32 v25, v104, v25, v105
	v_mul_f32_e32 v24, v24, v104
	s_waitcnt vmcnt(4)
	v_fma_f32 v25, v106, v25, v107
	v_mul_f32_e32 v24, v24, v106
	s_waitcnt vmcnt(3)
	v_fma_f32 v25, v108, v25, v109
	v_mul_f32_e32 v24, v24, v108
	s_waitcnt vmcnt(2)
	v_fma_f32 v25, v110, v25, v111
	v_mul_f32_e32 v24, v24, v110
	s_waitcnt vmcnt(1)
	v_fma_f32 v25, v112, v25, v113
	v_mul_f32_e32 v24, v24, v112
	s_waitcnt vmcnt(0)
	v_fma_f32 v25, v114, v25, v115
	v_mul_f32_e32 v24, v24, v114
	ds_write_b64 v22, v[24:25] offset:3584
	s_waitcnt lgkmcnt(0)
	s_barrier
	v_mov_b32_e32 v26, 0
	ds_read_b64 v[28:29], v22 offset:2048
	s_waitcnt lgkmcnt(0)
	v_fma_f32 v26, v28, v26, v29
	ds_read_b64 v[28:29], v22 offset:2560
	s_waitcnt lgkmcnt(0)
	v_fma_f32 v26, v28, v26, v29
	ds_read_b64 v[28:29], v22 offset:3072
	s_waitcnt lgkmcnt(0)
	v_fma_f32 v26, v28, v26, v29
	s_cmp_eq_u32 s99, 0
	s_cbranch_scc0 .Lcf_skip_7_0
	s_add_u32 s100, s68, 0x1630ec40
	s_addc_u32 s101, s69, 0
	global_store_dword v21, v26, s[100:101]
